# K-loops: dropped the dead second lgkmcnt(0) wait behind the barrier of sub-phases 2 and 3, which also lands all 128 MFMAs per loop body on 8-byte boundaries
# speedup vs baseline: 1.0010x; 1.0010x over previous
.LBB0_133:
	s_or_b32 s36, s61, 1
	s_lshl_b64 s[30:31], s[36:37], 7
	s_add_u32 s51, s0, s30
	s_addc_u32 s4, s1, s31
	s_add_i32 s36, s61, 2
	s_lshl_b64 s[30:31], s[36:37], 7
	s_add_u32 s5, s0, s30
	s_addc_u32 s6, s1, s31
	s_and_b64 vcc, s[58:59], exec
	s_cselect_b32 vcc_hi, s40, s6
	s_cselect_b32 vcc_lo, s41, s5
	s_add_u32 s5, s42, s30
	s_addc_u32 s6, s43, s31
	s_and_b64 s[30:31], s[58:59], exec
	s_cselect_b32 s59, s10, s6
	s_cselect_b32 s58, s11, s5
	s_add_i32 s5, 0, 0x10000
	s_add_i32 s6, 0, 0x14000
	v_add_u32_e32 v140, s5, v251
	v_add_u32_e32 v156, s6, v251
	ds_read_b128 v[128:131], v140
	ds_read_b128 v[132:135], v140 offset:1024
	ds_read_b128 v[136:139], v140 offset:2048
	ds_read_b128 v[140:143], v140 offset:3072
	ds_read_b128 v[144:147], v156
	ds_read_b128 v[148:151], v156 offset:1024
	ds_read_b128 v[152:155], v156 offset:2048
	ds_read_b128 v[156:159], v156 offset:3072
	s_add_u32 s30, s51, 0x40000
	s_addc_u32 s31, s4, 0
	v_lshl_add_u64 v[192:193], s[30:31], 0, v[216:217]
	s_add_i32 m0, s20, 0xc000
	ds_read_b128 v[160:163], v233
	ds_read_b128 v[164:167], v233 offset:1024
	ds_read_b128 v[168:171], v233 offset:2048
	ds_read_b128 v[172:175], v233 offset:3072
	ds_read_b128 v[176:179], v233 offset:4096
	ds_read_b128 v[180:183], v233 offset:5120
	ds_read_b128 v[184:187], v233 offset:6144
	ds_read_b128 v[188:191], v233 offset:7168
	global_load_lds_dwordx4 v[192:193], off
	v_lshl_add_u64 v[192:193], s[30:31], 0, v[218:219]
	s_add_i32 m0, s20, 0xe000
	s_nop 0
	global_load_lds_dwordx4 v[192:193], off
	s_waitcnt vmcnt(8)
	s_waitcnt lgkmcnt(0)
	s_barrier
	s_setprio 1
	s_waitcnt lgkmcnt(0)
	v_mfma_f32_16x16x32_bf16 v[124:127], v[128:131], v[160:163], v[124:127]
	v_mfma_f32_16x16x32_bf16 v[120:123], v[136:139], v[160:163], v[120:123]
	v_mfma_f32_16x16x32_bf16 v[116:119], v[128:131], v[168:171], v[116:119]
	v_mfma_f32_16x16x32_bf16 v[112:115], v[136:139], v[168:171], v[112:115]
	v_mfma_f32_16x16x32_bf16 v[108:111], v[128:131], v[176:179], v[108:111]
	v_mfma_f32_16x16x32_bf16 v[104:107], v[136:139], v[176:179], v[104:107]
	v_mfma_f32_16x16x32_bf16 v[100:103], v[128:131], v[184:187], v[100:103]
	v_mfma_f32_16x16x32_bf16 v[96:99], v[136:139], v[184:187], v[96:99]
	v_mfma_f32_16x16x32_bf16 v[124:127], v[132:135], v[164:167], v[124:127]
	v_mfma_f32_16x16x32_bf16 v[120:123], v[140:143], v[164:167], v[120:123]
	v_mfma_f32_16x16x32_bf16 v[116:119], v[132:135], v[172:175], v[116:119]
	v_mfma_f32_16x16x32_bf16 v[112:115], v[140:143], v[172:175], v[112:115]
	v_mfma_f32_16x16x32_bf16 v[108:111], v[132:135], v[180:183], v[108:111]
	v_mfma_f32_16x16x32_bf16 v[104:107], v[140:143], v[180:183], v[104:107]
	v_mfma_f32_16x16x32_bf16 v[100:103], v[132:135], v[188:191], v[100:103]
	v_mfma_f32_16x16x32_bf16 v[96:99], v[140:143], v[188:191], v[96:99]
	s_setprio 0
	s_setprio 1
	v_mfma_f32_16x16x32_bf16 v[92:95], v[144:147], v[160:163], v[92:95]
	v_mfma_f32_16x16x32_bf16 v[88:91], v[152:155], v[160:163], v[88:91]
	v_mfma_f32_16x16x32_bf16 v[84:87], v[144:147], v[168:171], v[84:87]
	v_mfma_f32_16x16x32_bf16 v[80:83], v[152:155], v[168:171], v[80:83]
	v_mfma_f32_16x16x32_bf16 v[76:79], v[144:147], v[176:179], v[76:79]
	v_mfma_f32_16x16x32_bf16 v[72:75], v[152:155], v[176:179], v[72:75]
	v_mfma_f32_16x16x32_bf16 v[68:71], v[144:147], v[184:187], v[68:71]
	v_mfma_f32_16x16x32_bf16 v[64:67], v[152:155], v[184:187], v[64:67]
	v_mfma_f32_16x16x32_bf16 v[92:95], v[148:151], v[164:167], v[92:95]
	v_mfma_f32_16x16x32_bf16 v[88:91], v[156:159], v[164:167], v[88:91]
	v_mfma_f32_16x16x32_bf16 v[84:87], v[148:151], v[172:175], v[84:87]
	v_mfma_f32_16x16x32_bf16 v[80:83], v[156:159], v[172:175], v[80:83]
	v_mfma_f32_16x16x32_bf16 v[76:79], v[148:151], v[180:183], v[76:79]
	v_mfma_f32_16x16x32_bf16 v[72:75], v[156:159], v[180:183], v[72:75]
	v_mfma_f32_16x16x32_bf16 v[68:71], v[148:151], v[188:191], v[68:71]
	v_mfma_f32_16x16x32_bf16 v[64:67], v[156:159], v[188:191], v[64:67]
	s_setprio 0
	s_barrier
	s_add_i32 s4, s5, s17
	v_lshl_add_u64 v[192:193], s[58:59], 0, v[216:217]
	s_mov_b32 m0, s4
	ds_read_b128 v[160:163], v233 offset:16384
	ds_read_b128 v[164:167], v233 offset:17408
	ds_read_b128 v[168:171], v233 offset:18432
	ds_read_b128 v[172:175], v233 offset:19456
	ds_read_b128 v[176:179], v233 offset:20480
	ds_read_b128 v[180:183], v233 offset:21504
	ds_read_b128 v[184:187], v233 offset:22528
	ds_read_b128 v[188:191], v233 offset:23552
	global_load_lds_dwordx4 v[192:193], off
	s_add_i32 m0, s4, 0x2000
	s_add_u32 s30, s58, 0x40000
	v_lshl_add_u64 v[194:195], s[58:59], 0, v[218:219]
	s_addc_u32 s31, s59, 0
	s_add_i32 s4, s6, s17
	global_load_lds_dwordx4 v[194:195], off
	v_lshl_add_u64 v[196:197], s[30:31], 0, v[216:217]
	s_mov_b32 m0, s4
	v_lshl_add_u64 v[198:199], vcc, 0, v[218:219]
	global_load_lds_dwordx4 v[196:197], off
	v_lshl_add_u64 v[196:197], s[30:31], 0, v[218:219]
	s_add_i32 m0, s4, 0x2000
	s_nop 0
	global_load_lds_dwordx4 v[196:197], off
	v_lshl_add_u64 v[196:197], vcc, 0, v[216:217]
	s_mov_b32 m0, s20
	s_nop 0
	global_load_lds_dwordx4 v[196:197], off
	s_mov_b32 m0, s21
	s_nop 0
	global_load_lds_dwordx4 v[198:199], off
	s_waitcnt vmcnt(8)
	s_waitcnt lgkmcnt(0)
	s_barrier
	s_setprio 1
	v_mfma_f32_16x16x32_bf16 v[60:63], v[128:131], v[160:163], v[60:63]
	v_mfma_f32_16x16x32_bf16 v[56:59], v[136:139], v[160:163], v[56:59]
	v_mfma_f32_16x16x32_bf16 v[52:55], v[128:131], v[168:171], v[52:55]
	v_mfma_f32_16x16x32_bf16 v[48:51], v[136:139], v[168:171], v[48:51]
	v_mfma_f32_16x16x32_bf16 v[44:47], v[128:131], v[176:179], v[44:47]
	v_mfma_f32_16x16x32_bf16 v[40:43], v[136:139], v[176:179], v[40:43]
	v_mfma_f32_16x16x32_bf16 v[36:39], v[128:131], v[184:187], v[36:39]
	v_mfma_f32_16x16x32_bf16 v[32:35], v[136:139], v[184:187], v[32:35]
	v_mfma_f32_16x16x32_bf16 v[60:63], v[132:135], v[164:167], v[60:63]
	v_mfma_f32_16x16x32_bf16 v[56:59], v[140:143], v[164:167], v[56:59]
	v_mfma_f32_16x16x32_bf16 v[52:55], v[132:135], v[172:175], v[52:55]
	v_mfma_f32_16x16x32_bf16 v[48:51], v[140:143], v[172:175], v[48:51]
	v_mfma_f32_16x16x32_bf16 v[44:47], v[132:135], v[180:183], v[44:47]
	v_mfma_f32_16x16x32_bf16 v[40:43], v[140:143], v[180:183], v[40:43]
	v_mfma_f32_16x16x32_bf16 v[36:39], v[132:135], v[188:191], v[36:39]
	v_mfma_f32_16x16x32_bf16 v[32:35], v[140:143], v[188:191], v[32:35]
	s_setprio 0
	s_setprio 1
	v_mfma_f32_16x16x32_bf16 v[28:31], v[144:147], v[160:163], v[28:31]
	v_mfma_f32_16x16x32_bf16 v[24:27], v[152:155], v[160:163], v[24:27]
	v_mfma_f32_16x16x32_bf16 v[20:23], v[144:147], v[168:171], v[20:23]
	v_mfma_f32_16x16x32_bf16 v[16:19], v[152:155], v[168:171], v[16:19]
	v_mfma_f32_16x16x32_bf16 v[12:15], v[144:147], v[176:179], v[12:15]
	v_mfma_f32_16x16x32_bf16 v[8:11], v[152:155], v[176:179], v[8:11]
	v_mfma_f32_16x16x32_bf16 v[4:7], v[144:147], v[184:187], v[4:7]
	v_mfma_f32_16x16x32_bf16 v[0:3], v[152:155], v[184:187], v[0:3]
	v_mfma_f32_16x16x32_bf16 v[28:31], v[148:151], v[164:167], v[28:31]
	v_mfma_f32_16x16x32_bf16 v[24:27], v[156:159], v[164:167], v[24:27]
	v_mfma_f32_16x16x32_bf16 v[20:23], v[148:151], v[172:175], v[20:23]
	v_mfma_f32_16x16x32_bf16 v[16:19], v[156:159], v[172:175], v[16:19]
	v_mfma_f32_16x16x32_bf16 v[12:15], v[148:151], v[180:183], v[12:15]
	v_mfma_f32_16x16x32_bf16 v[8:11], v[156:159], v[180:183], v[8:11]
	v_mfma_f32_16x16x32_bf16 v[4:7], v[148:151], v[188:191], v[4:7]
	v_mfma_f32_16x16x32_bf16 v[0:3], v[156:159], v[188:191], v[0:3]
	s_setprio 0
	s_barrier
	s_add_i32 s4, 0, 0x18000
	s_add_i32 s5, 0, 0x1c000
	v_add_u32_e32 v140, s4, v251
	v_add_u32_e32 v156, s5, v251
	ds_read_b128 v[128:131], v140
	ds_read_b128 v[132:135], v140 offset:1024
	ds_read_b128 v[136:139], v140 offset:2048
	ds_read_b128 v[140:143], v140 offset:3072
	ds_read_b128 v[144:147], v156
	ds_read_b128 v[148:151], v156 offset:1024
	ds_read_b128 v[152:155], v156 offset:2048
	ds_read_b128 v[156:159], v156 offset:3072
	s_add_u32 s30, vcc_lo, 0x40000
	s_addc_u32 s31, vcc_hi, 0
	s_mov_b32 m0, s24
	v_lshl_add_u64 v[200:201], s[30:31], 0, v[216:217]
	ds_read_b128 v[160:163], v233 offset:32768
	ds_read_b128 v[164:167], v233 offset:33792
	ds_read_b128 v[168:171], v233 offset:34816
	ds_read_b128 v[172:175], v233 offset:35840
	ds_read_b128 v[176:179], v233 offset:36864
	ds_read_b128 v[180:183], v233 offset:37888
	ds_read_b128 v[184:187], v233 offset:38912
	ds_read_b128 v[188:191], v233 offset:39936
	global_load_lds_dwordx4 v[200:201], off
	v_lshl_add_u64 v[200:201], s[30:31], 0, v[218:219]
	s_mov_b32 m0, s25
	s_nop 0
	global_load_lds_dwordx4 v[200:201], off
	s_waitcnt vmcnt(8)
	s_waitcnt lgkmcnt(0)
	s_barrier
	s_setprio 1
	v_mfma_f32_16x16x32_bf16 v[124:127], v[128:131], v[160:163], v[124:127]
	v_mfma_f32_16x16x32_bf16 v[120:123], v[136:139], v[160:163], v[120:123]
	v_mfma_f32_16x16x32_bf16 v[116:119], v[128:131], v[168:171], v[116:119]
	v_mfma_f32_16x16x32_bf16 v[112:115], v[136:139], v[168:171], v[112:115]
	v_mfma_f32_16x16x32_bf16 v[108:111], v[128:131], v[176:179], v[108:111]
	v_mfma_f32_16x16x32_bf16 v[104:107], v[136:139], v[176:179], v[104:107]
	v_mfma_f32_16x16x32_bf16 v[100:103], v[128:131], v[184:187], v[100:103]
	v_mfma_f32_16x16x32_bf16 v[96:99], v[136:139], v[184:187], v[96:99]
	v_mfma_f32_16x16x32_bf16 v[124:127], v[132:135], v[164:167], v[124:127]
	v_mfma_f32_16x16x32_bf16 v[120:123], v[140:143], v[164:167], v[120:123]
	v_mfma_f32_16x16x32_bf16 v[116:119], v[132:135], v[172:175], v[116:119]
	v_mfma_f32_16x16x32_bf16 v[112:115], v[140:143], v[172:175], v[112:115]
	v_mfma_f32_16x16x32_bf16 v[108:111], v[132:135], v[180:183], v[108:111]
	v_mfma_f32_16x16x32_bf16 v[104:107], v[140:143], v[180:183], v[104:107]
	v_mfma_f32_16x16x32_bf16 v[100:103], v[132:135], v[188:191], v[100:103]
	v_mfma_f32_16x16x32_bf16 v[96:99], v[140:143], v[188:191], v[96:99]
	s_setprio 0
	s_setprio 1
	v_mfma_f32_16x16x32_bf16 v[92:95], v[144:147], v[160:163], v[92:95]
	v_mfma_f32_16x16x32_bf16 v[88:91], v[152:155], v[160:163], v[88:91]
	v_mfma_f32_16x16x32_bf16 v[84:87], v[144:147], v[168:171], v[84:87]
	v_mfma_f32_16x16x32_bf16 v[80:83], v[152:155], v[168:171], v[80:83]
	v_mfma_f32_16x16x32_bf16 v[76:79], v[144:147], v[176:179], v[76:79]
	v_mfma_f32_16x16x32_bf16 v[72:75], v[152:155], v[176:179], v[72:75]
	v_mfma_f32_16x16x32_bf16 v[68:71], v[144:147], v[184:187], v[68:71]
	v_mfma_f32_16x16x32_bf16 v[64:67], v[152:155], v[184:187], v[64:67]
	v_mfma_f32_16x16x32_bf16 v[92:95], v[148:151], v[164:167], v[92:95]
	v_mfma_f32_16x16x32_bf16 v[88:91], v[156:159], v[164:167], v[88:91]
	v_mfma_f32_16x16x32_bf16 v[84:87], v[148:151], v[172:175], v[84:87]
	v_mfma_f32_16x16x32_bf16 v[80:83], v[156:159], v[172:175], v[80:83]
	v_mfma_f32_16x16x32_bf16 v[76:79], v[148:151], v[180:183], v[76:79]
	v_mfma_f32_16x16x32_bf16 v[72:75], v[156:159], v[180:183], v[72:75]
	v_mfma_f32_16x16x32_bf16 v[68:71], v[148:151], v[188:191], v[68:71]
	v_mfma_f32_16x16x32_bf16 v[64:67], v[156:159], v[188:191], v[64:67]
	s_setprio 0
	s_barrier
	s_add_i32 s4, s4, s17
	v_lshl_add_u64 v[192:193], v[192:193], 0, s[52:53]
	s_mov_b32 m0, s4
	ds_read_b128 v[160:163], v233 offset:49152
	ds_read_b128 v[164:167], v233 offset:50176
	ds_read_b128 v[168:171], v233 offset:51200
	ds_read_b128 v[172:175], v233 offset:52224
	ds_read_b128 v[176:179], v233 offset:53248
	ds_read_b128 v[180:183], v233 offset:54272
	ds_read_b128 v[184:187], v233 offset:55296
	ds_read_b128 v[188:191], v233 offset:56320
	global_load_lds_dwordx4 v[192:193], off
	s_add_i32 m0, s4, 0x2000
	s_add_u32 s30, s58, 0x40080
	v_lshl_add_u64 v[192:193], v[194:195], 0, s[52:53]
	s_addc_u32 s31, s59, 0
	s_add_i32 s4, s5, s17
	global_load_lds_dwordx4 v[192:193], off
	v_lshl_add_u64 v[192:193], s[30:31], 0, v[216:217]
	s_mov_b32 m0, s4
	s_nop 0
	global_load_lds_dwordx4 v[192:193], off
	v_lshl_add_u64 v[192:193], s[30:31], 0, v[218:219]
	s_add_i32 m0, s4, 0x2000
	s_nop 0
	global_load_lds_dwordx4 v[192:193], off
	v_lshl_add_u64 v[192:193], v[196:197], 0, s[52:53]
	s_mov_b32 m0, s15
	s_nop 0
	global_load_lds_dwordx4 v[192:193], off
	v_lshl_add_u64 v[192:193], v[198:199], 0, s[52:53]
	s_mov_b32 m0, s33
	s_nop 0
	global_load_lds_dwordx4 v[192:193], off
	s_waitcnt vmcnt(8)
	s_waitcnt lgkmcnt(0)
	s_barrier
	s_setprio 1
	s_waitcnt lgkmcnt(0)
	v_mfma_f32_16x16x32_bf16 v[60:63], v[128:131], v[160:163], v[60:63]
	v_mfma_f32_16x16x32_bf16 v[56:59], v[136:139], v[160:163], v[56:59]
	v_mfma_f32_16x16x32_bf16 v[52:55], v[128:131], v[168:171], v[52:55]
	v_mfma_f32_16x16x32_bf16 v[48:51], v[136:139], v[168:171], v[48:51]
	v_mfma_f32_16x16x32_bf16 v[44:47], v[128:131], v[176:179], v[44:47]
	v_mfma_f32_16x16x32_bf16 v[40:43], v[136:139], v[176:179], v[40:43]
	v_mfma_f32_16x16x32_bf16 v[36:39], v[128:131], v[184:187], v[36:39]
	v_mfma_f32_16x16x32_bf16 v[32:35], v[136:139], v[184:187], v[32:35]
	v_mfma_f32_16x16x32_bf16 v[60:63], v[132:135], v[164:167], v[60:63]
	v_mfma_f32_16x16x32_bf16 v[56:59], v[140:143], v[164:167], v[56:59]
	v_mfma_f32_16x16x32_bf16 v[52:55], v[132:135], v[172:175], v[52:55]
	v_mfma_f32_16x16x32_bf16 v[48:51], v[140:143], v[172:175], v[48:51]
	v_mfma_f32_16x16x32_bf16 v[44:47], v[132:135], v[180:183], v[44:47]
	v_mfma_f32_16x16x32_bf16 v[40:43], v[140:143], v[180:183], v[40:43]
	v_mfma_f32_16x16x32_bf16 v[36:39], v[132:135], v[188:191], v[36:39]
	v_mfma_f32_16x16x32_bf16 v[32:35], v[140:143], v[188:191], v[32:35]
	s_setprio 0
	s_setprio 1
	v_mfma_f32_16x16x32_bf16 v[28:31], v[144:147], v[160:163], v[28:31]
	v_mfma_f32_16x16x32_bf16 v[24:27], v[152:155], v[160:163], v[24:27]
	v_mfma_f32_16x16x32_bf16 v[20:23], v[144:147], v[168:171], v[20:23]
	v_mfma_f32_16x16x32_bf16 v[16:19], v[152:155], v[168:171], v[16:19]
	v_mfma_f32_16x16x32_bf16 v[12:15], v[144:147], v[176:179], v[12:15]
	v_mfma_f32_16x16x32_bf16 v[8:11], v[152:155], v[176:179], v[8:11]
	v_mfma_f32_16x16x32_bf16 v[4:7], v[144:147], v[184:187], v[4:7]
	v_mfma_f32_16x16x32_bf16 v[0:3], v[152:155], v[184:187], v[0:3]
	v_mfma_f32_16x16x32_bf16 v[28:31], v[148:151], v[164:167], v[28:31]
	v_mfma_f32_16x16x32_bf16 v[24:27], v[156:159], v[164:167], v[24:27]
	v_mfma_f32_16x16x32_bf16 v[20:23], v[148:151], v[172:175], v[20:23]
	v_mfma_f32_16x16x32_bf16 v[16:19], v[156:159], v[172:175], v[16:19]
	v_mfma_f32_16x16x32_bf16 v[12:15], v[148:151], v[180:183], v[12:15]
	v_mfma_f32_16x16x32_bf16 v[8:11], v[156:159], v[180:183], v[8:11]
	v_mfma_f32_16x16x32_bf16 v[4:7], v[148:151], v[188:191], v[4:7]
	v_mfma_f32_16x16x32_bf16 v[0:3], v[156:159], v[188:191], v[0:3]
	s_setprio 0
	s_barrier
	s_cmp_ge_i32 s36, s47
	s_mov_b32 s61, s36
	s_cbranch_scc1 .LBB0_147

.LBB0_453:
	s_add_u32 s31, s18, 0xfffc0080
	s_addc_u32 s46, s19, -1
	s_add_i32 s51, 0, 0x10000
	s_cmp_eq_u32 s30, 12
	s_cselect_b32 s49, s11, s46
	s_cselect_b32 s48, s10, s31
	s_cselect_b32 s47, s59, s16
	s_cselect_b32 s46, s58, s1
	s_add_i32 s31, 0, 0x14000
	v_add_u32_e32 v154, s51, v158
	v_add_u32_e32 v165, s31, v158
	ds_read_b128 v[128:131], v154
	ds_read_b128 v[132:135], v154 offset:1024
	ds_read_b128 v[150:153], v154 offset:2048
	ds_read_b128 v[154:157], v154 offset:3072
	ds_read_b128 v[166:169], v165
	ds_read_b128 v[170:173], v165 offset:1024
	ds_read_b128 v[174:177], v165 offset:2048
	ds_read_b128 v[178:181], v165 offset:3072
	v_lshl_add_u64 v[206:207], s[18:19], 0, v[146:147]
	s_add_i32 m0, s41, 0xc000
	ds_read_b128 v[182:185], v164
	ds_read_b128 v[186:189], v164 offset:1024
	ds_read_b128 v[190:193], v164 offset:2048
	ds_read_b128 v[194:197], v164 offset:3072
	ds_read_b128 v[198:201], v164 offset:4096
	ds_read_b128 v[202:205], v164 offset:5120
	ds_read_b128 v[216:219], v164 offset:6144
	ds_read_b128 v[224:227], v164 offset:7168
	global_load_lds_dwordx4 v[206:207], off
	v_lshl_add_u64 v[206:207], s[18:19], 0, v[148:149]
	s_add_i32 m0, s41, 0xe000
	s_nop 0
	global_load_lds_dwordx4 v[206:207], off
	s_waitcnt vmcnt(8)
	s_waitcnt lgkmcnt(0)
	s_barrier
	s_setprio 1
	s_waitcnt lgkmcnt(0)
	v_mfma_f32_16x16x32_bf16 v[124:127], v[128:131], v[182:185], v[124:127]
	v_mfma_f32_16x16x32_bf16 v[120:123], v[150:153], v[182:185], v[120:123]
	v_mfma_f32_16x16x32_bf16 v[108:111], v[128:131], v[190:193], v[108:111]
	v_mfma_f32_16x16x32_bf16 v[104:107], v[150:153], v[190:193], v[104:107]
	v_mfma_f32_16x16x32_bf16 v[92:95], v[128:131], v[198:201], v[92:95]
	v_mfma_f32_16x16x32_bf16 v[88:91], v[150:153], v[198:201], v[88:91]
	v_mfma_f32_16x16x32_bf16 v[76:79], v[128:131], v[216:219], v[76:79]
	v_mfma_f32_16x16x32_bf16 v[72:75], v[150:153], v[216:219], v[72:75]
	v_mfma_f32_16x16x32_bf16 v[124:127], v[132:135], v[186:189], v[124:127]
	v_mfma_f32_16x16x32_bf16 v[120:123], v[154:157], v[186:189], v[120:123]
	v_mfma_f32_16x16x32_bf16 v[108:111], v[132:135], v[194:197], v[108:111]
	v_mfma_f32_16x16x32_bf16 v[104:107], v[154:157], v[194:197], v[104:107]
	v_mfma_f32_16x16x32_bf16 v[92:95], v[132:135], v[202:205], v[92:95]
	v_mfma_f32_16x16x32_bf16 v[88:91], v[154:157], v[202:205], v[88:91]
	v_mfma_f32_16x16x32_bf16 v[76:79], v[132:135], v[224:227], v[76:79]
	v_mfma_f32_16x16x32_bf16 v[72:75], v[154:157], v[224:227], v[72:75]
	s_setprio 0
	s_setprio 1
	v_mfma_f32_16x16x32_bf16 v[116:119], v[166:169], v[182:185], v[116:119]
	v_mfma_f32_16x16x32_bf16 v[112:115], v[174:177], v[182:185], v[112:115]
	v_mfma_f32_16x16x32_bf16 v[100:103], v[166:169], v[190:193], v[100:103]
	v_mfma_f32_16x16x32_bf16 v[96:99], v[174:177], v[190:193], v[96:99]
	v_mfma_f32_16x16x32_bf16 v[84:87], v[166:169], v[198:201], v[84:87]
	v_mfma_f32_16x16x32_bf16 v[80:83], v[174:177], v[198:201], v[80:83]
	v_mfma_f32_16x16x32_bf16 v[68:71], v[166:169], v[216:219], v[68:71]
	v_mfma_f32_16x16x32_bf16 v[64:67], v[174:177], v[216:219], v[64:67]
	v_mfma_f32_16x16x32_bf16 v[116:119], v[170:173], v[186:189], v[116:119]
	v_mfma_f32_16x16x32_bf16 v[112:115], v[178:181], v[186:189], v[112:115]
	v_mfma_f32_16x16x32_bf16 v[100:103], v[170:173], v[194:197], v[100:103]
	v_mfma_f32_16x16x32_bf16 v[96:99], v[178:181], v[194:197], v[96:99]
	v_mfma_f32_16x16x32_bf16 v[84:87], v[170:173], v[202:205], v[84:87]
	v_mfma_f32_16x16x32_bf16 v[80:83], v[178:181], v[202:205], v[80:83]
	v_mfma_f32_16x16x32_bf16 v[68:71], v[170:173], v[224:227], v[68:71]
	v_mfma_f32_16x16x32_bf16 v[64:67], v[178:181], v[224:227], v[64:67]
	s_setprio 0
	s_barrier
	s_add_i32 s51, s51, s40
	v_lshl_add_u64 v[206:207], s[46:47], 0, v[136:137]
	s_mov_b32 m0, s51
	ds_read_b128 v[182:185], v164 offset:16384
	ds_read_b128 v[186:189], v164 offset:17408
	ds_read_b128 v[190:193], v164 offset:18432
	ds_read_b128 v[194:197], v164 offset:19456
	ds_read_b128 v[198:201], v164 offset:20480
	ds_read_b128 v[202:205], v164 offset:21504
	ds_read_b128 v[216:219], v164 offset:22528
	ds_read_b128 v[224:227], v164 offset:23552
	global_load_lds_dwordx4 v[206:207], off
	s_add_i32 m0, s51, 0x2000
	s_add_u32 s62, s46, 0x40000
	v_lshl_add_u64 v[250:251], s[46:47], 0, v[138:139]
	s_addc_u32 s63, s47, 0
	s_add_i32 s31, s31, s40
	global_load_lds_dwordx4 v[250:251], off
	v_lshl_add_u64 v[238:239], s[62:63], 0, v[136:137]
	s_mov_b32 m0, s31
	v_lshl_add_u64 v[244:245], s[48:49], 0, v[138:139]
	global_load_lds_dwordx4 v[238:239], off
	v_lshl_add_u64 v[238:239], s[62:63], 0, v[138:139]
	s_add_i32 m0, s31, 0x2000
	s_nop 0
	global_load_lds_dwordx4 v[238:239], off
	v_lshl_add_u64 v[238:239], s[48:49], 0, v[136:137]
	s_mov_b32 m0, s41
	s_nop 0
	global_load_lds_dwordx4 v[238:239], off
	s_mov_b32 m0, s33
	s_nop 0
	global_load_lds_dwordx4 v[244:245], off
	s_waitcnt vmcnt(8)
	s_waitcnt lgkmcnt(0)
	s_barrier
	s_setprio 1
	v_mfma_f32_16x16x32_bf16 v[60:63], v[128:131], v[182:185], v[60:63]
	v_mfma_f32_16x16x32_bf16 v[56:59], v[150:153], v[182:185], v[56:59]
	v_mfma_f32_16x16x32_bf16 v[44:47], v[128:131], v[190:193], v[44:47]
	v_mfma_f32_16x16x32_bf16 v[40:43], v[150:153], v[190:193], v[40:43]
	v_mfma_f32_16x16x32_bf16 v[28:31], v[128:131], v[198:201], v[28:31]
	v_mfma_f32_16x16x32_bf16 v[24:27], v[150:153], v[198:201], v[24:27]
	v_mfma_f32_16x16x32_bf16 v[12:15], v[128:131], v[216:219], v[12:15]
	v_mfma_f32_16x16x32_bf16 v[8:11], v[150:153], v[216:219], v[8:11]
	v_mfma_f32_16x16x32_bf16 v[60:63], v[132:135], v[186:189], v[60:63]
	v_mfma_f32_16x16x32_bf16 v[56:59], v[154:157], v[186:189], v[56:59]
	v_mfma_f32_16x16x32_bf16 v[44:47], v[132:135], v[194:197], v[44:47]
	v_mfma_f32_16x16x32_bf16 v[40:43], v[154:157], v[194:197], v[40:43]
	v_mfma_f32_16x16x32_bf16 v[28:31], v[132:135], v[202:205], v[28:31]
	v_mfma_f32_16x16x32_bf16 v[24:27], v[154:157], v[202:205], v[24:27]
	v_mfma_f32_16x16x32_bf16 v[12:15], v[132:135], v[224:227], v[12:15]
	v_mfma_f32_16x16x32_bf16 v[8:11], v[154:157], v[224:227], v[8:11]
	s_setprio 0
	s_setprio 1
	v_mfma_f32_16x16x32_bf16 v[52:55], v[166:169], v[182:185], v[52:55]
	v_mfma_f32_16x16x32_bf16 v[48:51], v[174:177], v[182:185], v[48:51]
	v_mfma_f32_16x16x32_bf16 v[36:39], v[166:169], v[190:193], v[36:39]
	v_mfma_f32_16x16x32_bf16 v[32:35], v[174:177], v[190:193], v[32:35]
	v_mfma_f32_16x16x32_bf16 v[20:23], v[166:169], v[198:201], v[20:23]
	v_mfma_f32_16x16x32_bf16 v[16:19], v[174:177], v[198:201], v[16:19]
	v_mfma_f32_16x16x32_bf16 v[4:7], v[166:169], v[216:219], v[4:7]
	v_mfma_f32_16x16x32_bf16 v[0:3], v[174:177], v[216:219], v[0:3]
	v_mfma_f32_16x16x32_bf16 v[52:55], v[170:173], v[186:189], v[52:55]
	v_mfma_f32_16x16x32_bf16 v[48:51], v[178:181], v[186:189], v[48:51]
	v_mfma_f32_16x16x32_bf16 v[36:39], v[170:173], v[194:197], v[36:39]
	v_mfma_f32_16x16x32_bf16 v[32:35], v[178:181], v[194:197], v[32:35]
	v_mfma_f32_16x16x32_bf16 v[20:23], v[170:173], v[202:205], v[20:23]
	v_mfma_f32_16x16x32_bf16 v[16:19], v[178:181], v[202:205], v[16:19]
	v_mfma_f32_16x16x32_bf16 v[4:7], v[170:173], v[224:227], v[4:7]
	v_mfma_f32_16x16x32_bf16 v[0:3], v[178:181], v[224:227], v[0:3]
	s_setprio 0
	s_barrier
	s_add_i32 s31, 0, 0x18000
	s_add_i32 s51, 0, 0x1c000
	v_add_u32_e32 v154, s31, v158
	v_add_u32_e32 v165, s51, v158
	ds_read_b128 v[128:131], v154
	ds_read_b128 v[132:135], v154 offset:1024
	ds_read_b128 v[150:153], v154 offset:2048
	ds_read_b128 v[154:157], v154 offset:3072
	ds_read_b128 v[166:169], v165
	ds_read_b128 v[170:173], v165 offset:1024
	ds_read_b128 v[174:177], v165 offset:2048
	ds_read_b128 v[178:181], v165 offset:3072
	s_add_u32 s48, s48, 0x40000
	s_addc_u32 s49, s49, 0
	s_mov_b32 m0, s15
	v_lshl_add_u64 v[246:247], s[48:49], 0, v[136:137]
	ds_read_b128 v[182:185], v164 offset:32768
	ds_read_b128 v[186:189], v164 offset:33792
	ds_read_b128 v[190:193], v164 offset:34816
	ds_read_b128 v[194:197], v164 offset:35840
	ds_read_b128 v[198:201], v164 offset:36864
	ds_read_b128 v[202:205], v164 offset:37888
	ds_read_b128 v[216:219], v164 offset:38912
	ds_read_b128 v[224:227], v164 offset:39936
	global_load_lds_dwordx4 v[246:247], off
	v_lshl_add_u64 v[246:247], s[48:49], 0, v[138:139]
	s_mov_b32 m0, s21
	s_nop 0
	global_load_lds_dwordx4 v[246:247], off
	s_waitcnt vmcnt(8)
	s_waitcnt lgkmcnt(0)
	s_barrier
	s_setprio 1
	v_mfma_f32_16x16x32_bf16 v[124:127], v[128:131], v[182:185], v[124:127]
	v_mfma_f32_16x16x32_bf16 v[120:123], v[150:153], v[182:185], v[120:123]
	v_mfma_f32_16x16x32_bf16 v[108:111], v[128:131], v[190:193], v[108:111]
	v_mfma_f32_16x16x32_bf16 v[104:107], v[150:153], v[190:193], v[104:107]
	v_mfma_f32_16x16x32_bf16 v[92:95], v[128:131], v[198:201], v[92:95]
	v_mfma_f32_16x16x32_bf16 v[88:91], v[150:153], v[198:201], v[88:91]
	v_mfma_f32_16x16x32_bf16 v[76:79], v[128:131], v[216:219], v[76:79]
	v_mfma_f32_16x16x32_bf16 v[72:75], v[150:153], v[216:219], v[72:75]
	v_mfma_f32_16x16x32_bf16 v[124:127], v[132:135], v[186:189], v[124:127]
	v_mfma_f32_16x16x32_bf16 v[120:123], v[154:157], v[186:189], v[120:123]
	v_mfma_f32_16x16x32_bf16 v[108:111], v[132:135], v[194:197], v[108:111]
	v_mfma_f32_16x16x32_bf16 v[104:107], v[154:157], v[194:197], v[104:107]
	v_mfma_f32_16x16x32_bf16 v[92:95], v[132:135], v[202:205], v[92:95]
	v_mfma_f32_16x16x32_bf16 v[88:91], v[154:157], v[202:205], v[88:91]
	v_mfma_f32_16x16x32_bf16 v[76:79], v[132:135], v[224:227], v[76:79]
	v_mfma_f32_16x16x32_bf16 v[72:75], v[154:157], v[224:227], v[72:75]
	s_setprio 0
	s_setprio 1
	v_mfma_f32_16x16x32_bf16 v[116:119], v[166:169], v[182:185], v[116:119]
	v_mfma_f32_16x16x32_bf16 v[112:115], v[174:177], v[182:185], v[112:115]
	v_mfma_f32_16x16x32_bf16 v[100:103], v[166:169], v[190:193], v[100:103]
	v_mfma_f32_16x16x32_bf16 v[96:99], v[174:177], v[190:193], v[96:99]
	v_mfma_f32_16x16x32_bf16 v[84:87], v[166:169], v[198:201], v[84:87]
	v_mfma_f32_16x16x32_bf16 v[80:83], v[174:177], v[198:201], v[80:83]
	v_mfma_f32_16x16x32_bf16 v[68:71], v[166:169], v[216:219], v[68:71]
	v_mfma_f32_16x16x32_bf16 v[64:67], v[174:177], v[216:219], v[64:67]
	v_mfma_f32_16x16x32_bf16 v[116:119], v[170:173], v[186:189], v[116:119]
	v_mfma_f32_16x16x32_bf16 v[112:115], v[178:181], v[186:189], v[112:115]
	v_mfma_f32_16x16x32_bf16 v[100:103], v[170:173], v[194:197], v[100:103]
	v_mfma_f32_16x16x32_bf16 v[96:99], v[178:181], v[194:197], v[96:99]
	v_mfma_f32_16x16x32_bf16 v[84:87], v[170:173], v[202:205], v[84:87]
	v_mfma_f32_16x16x32_bf16 v[80:83], v[178:181], v[202:205], v[80:83]
	v_mfma_f32_16x16x32_bf16 v[68:71], v[170:173], v[224:227], v[68:71]
	v_mfma_f32_16x16x32_bf16 v[64:67], v[178:181], v[224:227], v[64:67]
	s_setprio 0
	s_barrier
	s_add_i32 s31, s31, s40
	v_lshl_add_u64 v[206:207], v[206:207], 0, s[52:53]
	s_mov_b32 m0, s31
	ds_read_b128 v[182:185], v164 offset:49152
	ds_read_b128 v[186:189], v164 offset:50176
	ds_read_b128 v[190:193], v164 offset:51200
	ds_read_b128 v[194:197], v164 offset:52224
	ds_read_b128 v[198:201], v164 offset:53248
	ds_read_b128 v[202:205], v164 offset:54272
	ds_read_b128 v[216:219], v164 offset:55296
	ds_read_b128 v[224:227], v164 offset:56320
	global_load_lds_dwordx4 v[206:207], off
	s_add_i32 m0, s31, 0x2000
	s_add_u32 s46, s46, 0x40080
	v_lshl_add_u64 v[206:207], v[250:251], 0, s[52:53]
	s_addc_u32 s47, s47, 0
	s_add_i32 s31, s51, s40
	global_load_lds_dwordx4 v[206:207], off
	v_lshl_add_u64 v[206:207], s[46:47], 0, v[136:137]
	s_mov_b32 m0, s31
	s_nop 0
	global_load_lds_dwordx4 v[206:207], off
	v_lshl_add_u64 v[206:207], s[46:47], 0, v[138:139]
	s_add_i32 m0, s31, 0x2000
	s_nop 0
	global_load_lds_dwordx4 v[206:207], off
	v_lshl_add_u64 v[206:207], v[238:239], 0, s[52:53]
	s_mov_b32 m0, s24
	s_nop 0
	global_load_lds_dwordx4 v[206:207], off
	v_lshl_add_u64 v[206:207], v[244:245], 0, s[52:53]
	s_mov_b32 m0, s25
	s_nop 0
	global_load_lds_dwordx4 v[206:207], off
	s_waitcnt vmcnt(8)
	s_waitcnt lgkmcnt(0)
	s_barrier
	s_setprio 1
	s_waitcnt lgkmcnt(0)
	v_mfma_f32_16x16x32_bf16 v[60:63], v[128:131], v[182:185], v[60:63]
	v_mfma_f32_16x16x32_bf16 v[56:59], v[150:153], v[182:185], v[56:59]
	v_mfma_f32_16x16x32_bf16 v[44:47], v[128:131], v[190:193], v[44:47]
	v_mfma_f32_16x16x32_bf16 v[40:43], v[150:153], v[190:193], v[40:43]
	v_mfma_f32_16x16x32_bf16 v[28:31], v[128:131], v[198:201], v[28:31]
	v_mfma_f32_16x16x32_bf16 v[24:27], v[150:153], v[198:201], v[24:27]
	v_mfma_f32_16x16x32_bf16 v[12:15], v[128:131], v[216:219], v[12:15]
	v_mfma_f32_16x16x32_bf16 v[8:11], v[150:153], v[216:219], v[8:11]
	v_mfma_f32_16x16x32_bf16 v[60:63], v[132:135], v[186:189], v[60:63]
	v_mfma_f32_16x16x32_bf16 v[56:59], v[154:157], v[186:189], v[56:59]
	v_mfma_f32_16x16x32_bf16 v[44:47], v[132:135], v[194:197], v[44:47]
	v_mfma_f32_16x16x32_bf16 v[40:43], v[154:157], v[194:197], v[40:43]
	v_mfma_f32_16x16x32_bf16 v[28:31], v[132:135], v[202:205], v[28:31]
	v_mfma_f32_16x16x32_bf16 v[24:27], v[154:157], v[202:205], v[24:27]
	v_mfma_f32_16x16x32_bf16 v[12:15], v[132:135], v[224:227], v[12:15]
	v_mfma_f32_16x16x32_bf16 v[8:11], v[154:157], v[224:227], v[8:11]
	s_setprio 0
	s_setprio 1
	v_mfma_f32_16x16x32_bf16 v[52:55], v[166:169], v[182:185], v[52:55]
	v_mfma_f32_16x16x32_bf16 v[48:51], v[174:177], v[182:185], v[48:51]
	v_mfma_f32_16x16x32_bf16 v[36:39], v[166:169], v[190:193], v[36:39]
	v_mfma_f32_16x16x32_bf16 v[32:35], v[174:177], v[190:193], v[32:35]
	v_mfma_f32_16x16x32_bf16 v[20:23], v[166:169], v[198:201], v[20:23]
	v_mfma_f32_16x16x32_bf16 v[16:19], v[174:177], v[198:201], v[16:19]
	v_mfma_f32_16x16x32_bf16 v[4:7], v[166:169], v[216:219], v[4:7]
	v_mfma_f32_16x16x32_bf16 v[0:3], v[174:177], v[216:219], v[0:3]
	v_mfma_f32_16x16x32_bf16 v[52:55], v[170:173], v[186:189], v[52:55]
	v_mfma_f32_16x16x32_bf16 v[48:51], v[178:181], v[186:189], v[48:51]
	v_mfma_f32_16x16x32_bf16 v[36:39], v[170:173], v[194:197], v[36:39]
	v_mfma_f32_16x16x32_bf16 v[32:35], v[178:181], v[194:197], v[32:35]
	v_mfma_f32_16x16x32_bf16 v[20:23], v[170:173], v[202:205], v[20:23]
	v_mfma_f32_16x16x32_bf16 v[16:19], v[178:181], v[202:205], v[16:19]
	v_mfma_f32_16x16x32_bf16 v[4:7], v[170:173], v[224:227], v[4:7]
	v_mfma_f32_16x16x32_bf16 v[0:3], v[178:181], v[224:227], v[0:3]
	s_setprio 0
	s_barrier
	s_add_i32 s30, s30, 2
	s_add_u32 s18, s18, 0x100
	s_addc_u32 s19, s19, 0
	s_add_u32 s1, s1, 0x100
	s_addc_u32 s16, s16, 0
	s_cmp_gt_u32 s30, 13
	s_cbranch_scc0 .LBB0_453
	s_and_b64 vcc, exec, s[64:65]
	s_cbranch_vccz .LBB0_456
	s_barrier
